# final RMSNorm phase hand-rewritten: norm weights kept in registers, next row's loads in flight during this row's math and stores, counted vmcnt
# speedup vs baseline: 1.0018x; 1.0010x over previous
.LBB0_1240:
	s_cmp_lt_i32 s84, 12
	s_cselect_b64 s[0:1], -1, 0
	s_cmp_gt_i32 s85, 11
	s_cselect_b64 s[2:3], -1, 0
	s_and_b64 s[0:1], s[0:1], s[2:3]
	s_andn2_b64 vcc, exec, s[0:1]
	s_cbranch_vccnz .LBB0_1296
	s_waitcnt vmcnt(0)
	v_lshl_add_u32 v0, s33, 3, v239
	s_movk_i32 s14, 0x4000
	v_cmp_gt_i32_e32 vcc, s14, v0
	s_and_saveexec_b64 s[2:3], vcc
	s_cbranch_execz .LBB0_1246
	v_readlane_b32 s20, v254, 25
	v_readlane_b32 s21, v254, 26
	v_readlane_b32 s0, v254, 0
	v_and_b32_e32 v1, 63, v238
	v_readfirstlane_b32 s12, v0
	v_lshlrev_b32_e32 v6, 4, v1
	v_lshlrev_b32_e32 v7, 3, v1
	v_add_u32_e32 v8, 0x1000, v6
	s_lshl_b32 s4, s0, 3
	global_load_dwordx4 v[110:113], v6, s[38:39]
	global_load_dwordx4 v[114:117], v6, s[38:39] offset:1024
	global_load_dwordx4 v[118:121], v6, s[38:39] offset:2048
	global_load_dwordx4 v[122:125], v6, s[38:39] offset:3072
	global_load_dwordx4 v[126:129], v8, s[38:39]
	global_load_dwordx4 v[130:133], v8, s[38:39] offset:1024
	global_load_dwordx4 v[134:137], v8, s[38:39] offset:2048
	global_load_dwordx4 v[138:141], v8, s[38:39] offset:3072
	s_lshl_b32 s13, s12, 12
	s_add_u32 s16, s20, s13
	s_addc_u32 s17, s21, 0
	s_lshl_b32 s13, s12, 13
	s_add_u32 s18, s40, s13
	s_addc_u32 s19, s41, 0
	s_lshl_b32 s22, s4, 12
	s_lshl_b32 s23, s4, 13
	global_load_dwordx2 v[142:143], v7, s[16:17] nt
	global_load_dwordx2 v[144:145], v7, s[16:17] offset:512 nt
	global_load_dwordx2 v[146:147], v7, s[16:17] offset:1024 nt
	global_load_dwordx2 v[148:149], v7, s[16:17] offset:1536 nt
	global_load_dwordx2 v[150:151], v7, s[16:17] offset:2048 nt
	global_load_dwordx2 v[152:153], v7, s[16:17] offset:2560 nt
	global_load_dwordx2 v[154:155], v7, s[16:17] offset:3072 nt
	global_load_dwordx2 v[156:157], v7, s[16:17] offset:3584 nt
	v_xor_b32_e32 v200, 16, v1
	v_xor_b32_e32 v201, 32, v1
	v_lshlrev_b32_e32 v200, 2, v200
	v_lshlrev_b32_e32 v201, 2, v201
	v_mov_b32_e32 v202, 0x358637bd
	s_waitcnt vmcnt(0)
	s_branch .Lfin_have
.Lfin_loop:
	s_waitcnt vmcnt(8)
.Lfin_have:
	v_cvt_f32_f16_e32 v160, v142
	v_cvt_f32_f16_sdwa v161, v142 dst_sel:DWORD dst_unused:UNUSED_PAD src0_sel:WORD_1
	v_cvt_f32_f16_e32 v162, v143
	v_cvt_f32_f16_sdwa v163, v143 dst_sel:DWORD dst_unused:UNUSED_PAD src0_sel:WORD_1
	v_cvt_f32_f16_e32 v164, v144
	v_cvt_f32_f16_sdwa v165, v144 dst_sel:DWORD dst_unused:UNUSED_PAD src0_sel:WORD_1
	v_cvt_f32_f16_e32 v166, v145
	v_cvt_f32_f16_sdwa v167, v145 dst_sel:DWORD dst_unused:UNUSED_PAD src0_sel:WORD_1
	v_cvt_f32_f16_e32 v168, v146
	v_cvt_f32_f16_sdwa v169, v146 dst_sel:DWORD dst_unused:UNUSED_PAD src0_sel:WORD_1
	v_cvt_f32_f16_e32 v170, v147
	v_cvt_f32_f16_sdwa v171, v147 dst_sel:DWORD dst_unused:UNUSED_PAD src0_sel:WORD_1
	v_cvt_f32_f16_e32 v172, v148
	v_cvt_f32_f16_sdwa v173, v148 dst_sel:DWORD dst_unused:UNUSED_PAD src0_sel:WORD_1
	v_cvt_f32_f16_e32 v174, v149
	v_cvt_f32_f16_sdwa v175, v149 dst_sel:DWORD dst_unused:UNUSED_PAD src0_sel:WORD_1
	v_cvt_f32_f16_e32 v176, v150
	v_cvt_f32_f16_sdwa v177, v150 dst_sel:DWORD dst_unused:UNUSED_PAD src0_sel:WORD_1
	v_cvt_f32_f16_e32 v178, v151
	v_cvt_f32_f16_sdwa v179, v151 dst_sel:DWORD dst_unused:UNUSED_PAD src0_sel:WORD_1
	v_cvt_f32_f16_e32 v180, v152
	v_cvt_f32_f16_sdwa v181, v152 dst_sel:DWORD dst_unused:UNUSED_PAD src0_sel:WORD_1
	v_cvt_f32_f16_e32 v182, v153
	v_cvt_f32_f16_sdwa v183, v153 dst_sel:DWORD dst_unused:UNUSED_PAD src0_sel:WORD_1
	v_cvt_f32_f16_e32 v184, v154
	v_cvt_f32_f16_sdwa v185, v154 dst_sel:DWORD dst_unused:UNUSED_PAD src0_sel:WORD_1
	v_cvt_f32_f16_e32 v186, v155
	v_cvt_f32_f16_sdwa v187, v155 dst_sel:DWORD dst_unused:UNUSED_PAD src0_sel:WORD_1
	v_cvt_f32_f16_e32 v188, v156
	v_cvt_f32_f16_sdwa v189, v156 dst_sel:DWORD dst_unused:UNUSED_PAD src0_sel:WORD_1
	v_cvt_f32_f16_e32 v190, v157
	v_cvt_f32_f16_sdwa v191, v157 dst_sel:DWORD dst_unused:UNUSED_PAD src0_sel:WORD_1
	s_add_i32 s12, s12, s4
	s_add_u32 s16, s16, s22
	s_addc_u32 s17, s17, 0
	s_cmpk_lt_i32 s12, 0x4000
	s_cbranch_scc0 .Lfin_nonext
	global_load_dwordx2 v[142:143], v7, s[16:17] nt
	global_load_dwordx2 v[144:145], v7, s[16:17] offset:512 nt
	global_load_dwordx2 v[146:147], v7, s[16:17] offset:1024 nt
	global_load_dwordx2 v[148:149], v7, s[16:17] offset:1536 nt
	global_load_dwordx2 v[150:151], v7, s[16:17] offset:2048 nt
	global_load_dwordx2 v[152:153], v7, s[16:17] offset:2560 nt
	global_load_dwordx2 v[154:155], v7, s[16:17] offset:3072 nt
	global_load_dwordx2 v[156:157], v7, s[16:17] offset:3584 nt
.Lfin_nonext:
	v_mul_f32_e32 v192, v160, v160
	v_mul_f32_e32 v193, v161, v161
	v_mul_f32_e32 v194, v162, v162
	v_mul_f32_e32 v195, v163, v163
	v_fmac_f32_e32 v192, v164, v164
	v_fmac_f32_e32 v193, v165, v165
	v_fmac_f32_e32 v194, v166, v166
	v_fmac_f32_e32 v195, v167, v167
	v_fmac_f32_e32 v192, v168, v168
	v_fmac_f32_e32 v193, v169, v169
	v_fmac_f32_e32 v194, v170, v170
	v_fmac_f32_e32 v195, v171, v171
	v_fmac_f32_e32 v192, v172, v172
	v_fmac_f32_e32 v193, v173, v173
	v_fmac_f32_e32 v194, v174, v174
	v_fmac_f32_e32 v195, v175, v175
	v_fmac_f32_e32 v192, v176, v176
	v_fmac_f32_e32 v193, v177, v177
	v_fmac_f32_e32 v194, v178, v178
	v_fmac_f32_e32 v195, v179, v179
	v_fmac_f32_e32 v192, v180, v180
	v_fmac_f32_e32 v193, v181, v181
	v_fmac_f32_e32 v194, v182, v182
	v_fmac_f32_e32 v195, v183, v183
	v_fmac_f32_e32 v192, v184, v184
	v_fmac_f32_e32 v193, v185, v185
	v_fmac_f32_e32 v194, v186, v186
	v_fmac_f32_e32 v195, v187, v187
	v_fmac_f32_e32 v192, v188, v188
	v_fmac_f32_e32 v193, v189, v189
	v_fmac_f32_e32 v194, v190, v190
	v_fmac_f32_e32 v195, v191, v191
	v_add_f32_e32 v192, v192, v193
	v_add_f32_e32 v194, v194, v195
	s_nop 0
	v_add_f32_e32 v192, v192, v194
	s_nop 1
	v_add_f32_dpp v192, v192, v192 quad_perm:[1,0,3,2] row_mask:0xf bank_mask:0xf bound_ctrl:1
	s_nop 1
	v_add_f32_dpp v192, v192, v192 quad_perm:[2,3,0,1] row_mask:0xf bank_mask:0xf bound_ctrl:1
	s_nop 1
	v_add_f32_dpp v192, v192, v192 row_half_mirror row_mask:0xf bank_mask:0xf bound_ctrl:1
	s_nop 1
	v_add_f32_dpp v192, v192, v192 row_mirror row_mask:0xf bank_mask:0xf bound_ctrl:1
	ds_bpermute_b32 v193, v200, v192
	s_waitcnt lgkmcnt(0)
	v_add_f32_e32 v192, v192, v193
	ds_bpermute_b32 v193, v201, v192
	s_waitcnt lgkmcnt(0)
	v_add_f32_e32 v192, v192, v193
	v_fmamk_f32 v192, v192, 0x3a000000, v202
	v_rsq_f32_e32 v192, v192
	s_nop 0
	v_mul_f32_e32 v196, v160, v192
	v_mul_f32_e32 v197, v161, v192
	v_mul_f32_e32 v198, v162, v192
	v_mul_f32_e32 v199, v163, v192
	v_mul_f32_e32 v196, v110, v196
	v_mul_f32_e32 v197, v111, v197
	v_mul_f32_e32 v198, v112, v198
	v_mul_f32_e32 v199, v113, v199
	global_store_dwordx4 v6, v[196:199], s[18:19] nt
	v_mul_f32_e32 v204, v164, v192
	v_mul_f32_e32 v205, v165, v192
	v_mul_f32_e32 v206, v166, v192
	v_mul_f32_e32 v207, v167, v192
	v_mul_f32_e32 v204, v114, v204
	v_mul_f32_e32 v205, v115, v205
	v_mul_f32_e32 v206, v116, v206
	v_mul_f32_e32 v207, v117, v207
	global_store_dwordx4 v6, v[204:207], s[18:19] offset:1024 nt
	v_mul_f32_e32 v196, v168, v192
	v_mul_f32_e32 v197, v169, v192
	v_mul_f32_e32 v198, v170, v192
	v_mul_f32_e32 v199, v171, v192
	v_mul_f32_e32 v196, v118, v196
	v_mul_f32_e32 v197, v119, v197
	v_mul_f32_e32 v198, v120, v198
	v_mul_f32_e32 v199, v121, v199
	global_store_dwordx4 v6, v[196:199], s[18:19] offset:2048 nt
	v_mul_f32_e32 v204, v172, v192
	v_mul_f32_e32 v205, v173, v192
	v_mul_f32_e32 v206, v174, v192
	v_mul_f32_e32 v207, v175, v192
	v_mul_f32_e32 v204, v122, v204
	v_mul_f32_e32 v205, v123, v205
	v_mul_f32_e32 v206, v124, v206
	v_mul_f32_e32 v207, v125, v207
	global_store_dwordx4 v6, v[204:207], s[18:19] offset:3072 nt
	v_mul_f32_e32 v196, v176, v192
	v_mul_f32_e32 v197, v177, v192
	v_mul_f32_e32 v198, v178, v192
	v_mul_f32_e32 v199, v179, v192
	v_mul_f32_e32 v196, v126, v196
	v_mul_f32_e32 v197, v127, v197
	v_mul_f32_e32 v198, v128, v198
	v_mul_f32_e32 v199, v129, v199
	global_store_dwordx4 v8, v[196:199], s[18:19] nt
	v_mul_f32_e32 v204, v180, v192
	v_mul_f32_e32 v205, v181, v192
	v_mul_f32_e32 v206, v182, v192
	v_mul_f32_e32 v207, v183, v192
	v_mul_f32_e32 v204, v130, v204
	v_mul_f32_e32 v205, v131, v205
	v_mul_f32_e32 v206, v132, v206
	v_mul_f32_e32 v207, v133, v207
	global_store_dwordx4 v8, v[204:207], s[18:19] offset:1024 nt
	v_mul_f32_e32 v196, v184, v192
	v_mul_f32_e32 v197, v185, v192
	v_mul_f32_e32 v198, v186, v192
	v_mul_f32_e32 v199, v187, v192
	v_mul_f32_e32 v196, v134, v196
	v_mul_f32_e32 v197, v135, v197
	v_mul_f32_e32 v198, v136, v198
	v_mul_f32_e32 v199, v137, v199
	global_store_dwordx4 v8, v[196:199], s[18:19] offset:2048 nt
	v_mul_f32_e32 v204, v188, v192
	v_mul_f32_e32 v205, v189, v192
	v_mul_f32_e32 v206, v190, v192
	v_mul_f32_e32 v207, v191, v192
	v_mul_f32_e32 v204, v138, v204
	v_mul_f32_e32 v205, v139, v205
	v_mul_f32_e32 v206, v140, v206
	v_mul_f32_e32 v207, v141, v207
	global_store_dwordx4 v8, v[204:207], s[18:19] offset:3072 nt
	s_add_u32 s18, s18, s23
	s_addc_u32 s19, s19, 0
	s_cmpk_lt_i32 s12, 0x4000
	s_cbranch_scc1 .Lfin_loop
